# phase 0: s5 parameter block B-bar computation loads b_re/b_im as 8 dwordx4 instead of 64 serialized dword round trips
# baseline (speedup 1.0000x reference)
; __device__ __forceinline__ void phase_s5_params(const Fr& F) {
;     ...
;     const float lr = F.a->in[27][idx], li = F.a->in[28][idx], step = expf(F.a->in[29][s * 64 + g]);
;     const float mag = expf(lr * step), ar = mag * cosf(li * step), ai = mag * sinf(li * step), den = lr * lr + li * li;
;     const float qr = ((ar - 1.f) * lr + ai * li) / den, qi = (ai * lr - (ar - 1.f) * li) / den;
;     float pr = ar, pi = ai;
;     for (int i = 0; i < 6; ++i) { const float nr = pr * pr - pi * pi, ni = 2.f * pr * pi; pr = nr; pi = ni; }
;     float* A = (float*)(F.ws + OFF_S5A) + idx * 4; A[0] = ar; A[1] = ai; A[2] = pr; A[3] = pi;
;     float* BB = (float*)(F.ws + OFF_BB) + (size_t)idx * 32;
;     const float* br = F.a->in[30] + ((size_t)g * 64 + p) * 16; const float* bi = F.a->in[31] + ((size_t)g * 64 + p) * 16;
;     for (int c = 0; c < 16; ++c) { BB[c] = qr * br[c] - qi * bi[c]; BB[16 + c] = qr * bi[c] + qi * br[c]; }
.LBB0_34:
	s_or_b64 exec, exec, s[6:7]
	s_waitcnt vmcnt(0)
	v_mul_f32_e32 v7, v4, v7
	s_mov_b32 s3, 0x3fb8aa3b
	v_mul_f32_e32 v13, 0x3fb8aa3b, v7
	v_fma_f32 v14, v7, s3, -v13
	v_rndne_f32_e32 v15, v13
	v_fmamk_f32 v14, v7, 0x32a5705f, v14
	v_sub_f32_e32 v13, v13, v15
	v_add_f32_e32 v13, v13, v14
	v_exp_f32_e32 v13, v13
	v_cvt_i32_f32_e32 v14, v15
	s_mov_b32 s3, 0xc2ce8ed0
	v_cmp_ngt_f32_e32 vcc, s3, v7
	s_mov_b32 s3, 0x42b17218
	v_ldexp_f32 v13, v13, v14
	v_cndmask_b32_e32 v13, 0, v13, vcc
	v_mov_b32_e32 v14, 0x7f800000
	v_cmp_nlt_f32_e32 vcc, s3, v7
	v_mul_f32_e32 v7, v9, v9
	v_mov_b32_e32 v15, 0x3c0881c4
	v_cndmask_b32_e32 v13, v14, v13, vcc
	v_fmamk_f32 v14, v7, 0xb94c1982, v15
	v_fmaak_f32 v14, v7, v14, 0xbe2aaa9d
	v_mul_f32_e32 v14, v7, v14
	v_mov_b32_e32 v17, 0xbab64f3b
	v_fmac_f32_e32 v9, v9, v14
	v_fmamk_f32 v14, v7, 0x37d75334, v17
	v_fmaak_f32 v14, v7, v14, 0x3d2aabf7
	v_fmaak_f32 v14, v7, v14, 0xbf000004
	v_fma_f32 v7, v7, v14, 1.0
	v_and_b32_e32 v14, 1, v8
	v_cmp_eq_u32_e32 vcc, 0, v14
	v_lshlrev_b32_e32 v8, 30, v8
	s_brev_b32 s3, 1
	v_cndmask_b32_e64 v7, -v9, v7, vcc
	v_bitop3_b32 v7, v8, v7, s3 bitop3:0x6c
	s_movk_i32 s3, 0x1f8
	v_mov_b32_e32 v8, 0x7fc00000
	v_cmp_class_f32_e64 vcc, v5, s3
	v_mov_b32_e32 v16, 0xbe2aaa9d
	v_mov_b32_e32 v18, 0x3d2aabf7
	v_cndmask_b32_e32 v9, v8, v7, vcc
	v_mul_f32_e32 v7, v12, v12
	v_fmac_f32_e32 v15, 0xb94c1982, v7
	v_fmac_f32_e32 v16, v7, v15
	v_fmac_f32_e32 v17, 0x37d75334, v7
	v_mov_b32_e32 v19, 0xbf000004
	v_mul_f32_e32 v15, v7, v16
	v_fmac_f32_e32 v18, v7, v17
	v_fmac_f32_e32 v12, v12, v15
	v_fmac_f32_e32 v19, v7, v18
	v_and_b32_e32 v15, 1, v11
	v_lshlrev_b32_e32 v11, 30, v11
	v_fma_f32 v7, v7, v19, 1.0
	v_cmp_eq_u32_e64 s[6:7], 0, v15
	v_and_b32_e32 v11, 0x80000000, v11
	v_xor_b32_e32 v5, v6, v5
	v_cndmask_b32_e64 v7, v7, v12, s[6:7]
	v_xor_b32_e32 v5, v5, v11
	v_xor_b32_e32 v5, v5, v7
	v_mul_f32_e32 v14, v13, v9
	v_cndmask_b32_e32 v5, v8, v5, vcc
	v_mul_f32_e32 v15, v13, v5
	v_add_f32_e32 v6, v14, v14
	v_mul_f32_e32 v5, v15, v15
	v_mul_f32_e32 v6, v6, v15
	v_fma_f32 v5, v14, v14, -v5
	v_mul_f32_e32 v7, v6, v6
	v_fma_f32 v7, v5, v5, -v7
	v_add_f32_e32 v5, v5, v5
	v_mul_f32_e32 v5, v6, v5
	v_mul_f32_e32 v6, v5, v5
	v_fma_f32 v6, v7, v7, -v6
	v_add_f32_e32 v7, v7, v7
	v_mul_f32_e32 v5, v5, v7
	v_mul_f32_e32 v7, v5, v5
	v_fma_f32 v7, v6, v6, -v7
	v_add_f32_e32 v6, v6, v6
	v_mul_f32_e32 v5, v5, v6
	v_mul_f32_e32 v6, v5, v5
	v_fma_f32 v6, v7, v7, -v6
	v_add_f32_e32 v7, v7, v7
	v_mul_f32_e32 v5, v5, v7
	v_mul_f32_e32 v7, v5, v5
	v_fma_f32 v16, v6, v6, -v7
	v_add_f32_e32 v6, v6, v6
	v_mul_f32_e32 v17, v5, v6
	v_lshlrev_b32_e32 v6, 2, v2
	v_ashrrev_i32_e32 v7, 31, v6
	s_load_dwordx4 s[8:11], s[0:1], 0xf0
	v_lshl_add_u64 v[6:7], v[6:7], 2, s[26:27]
	s_mov_b32 s3, 0x40000
	v_add_co_u32_e32 v6, vcc, s3, v6
	v_lshlrev_b32_e32 v5, 6, v128
	s_nop 0
	v_addc_co_u32_e32 v7, vcc, 0, v7, vcc
	v_and_b32_e32 v5, 0xfc0, v5
	global_store_dwordx4 v[6:7], v[14:17], off
	v_lshl_or_b32 v6, v10, 12, v5
	s_waitcnt lgkmcnt(0)
	global_load_dword v5, v6, s[10:11]
	global_load_dword v7, v6, s[8:9]
	v_mul_f32_e32 v8, v1, v1
	v_fma_f32 v9, v13, v9, -1.0
	v_mul_f32_e32 v10, v1, v15
	v_fmac_f32_e32 v10, v4, v9
	v_fmac_f32_e32 v8, v4, v4
	v_div_scale_f32 v11, s[6:7], v8, v8, v10
	v_rcp_f32_e32 v12, v11
	v_mul_f32_e32 v1, v1, v9
	v_fma_f32 v1, v4, v15, -v1
	v_lshlrev_b64 v[2:3], 7, v[2:3]
	v_fma_f32 v4, -v11, v12, 1.0
	v_fmac_f32_e32 v12, v4, v12
	v_div_scale_f32 v4, vcc, v10, v8, v10
	v_mul_f32_e32 v9, v4, v12
	v_fma_f32 v13, -v11, v9, v4
	v_fmac_f32_e32 v9, v13, v12
	v_fma_f32 v4, -v11, v9, v4
	v_div_scale_f32 v11, s[6:7], v8, v8, v1
	v_rcp_f32_e32 v13, v11
	v_div_fmas_f32 v4, v4, v12, v9
	v_div_fixup_f32 v9, v4, v8, v10
	v_lshl_add_u64 v[2:3], s[26:27], 0, v[2:3]
	v_fma_f32 v4, -v11, v13, 1.0
	v_fmac_f32_e32 v13, v4, v13
	v_div_scale_f32 v4, vcc, v1, v8, v1
	v_mul_f32_e32 v10, v4, v13
	v_fma_f32 v12, -v11, v10, v4
	v_fmac_f32_e32 v10, v12, v13
	v_fma_f32 v4, -v11, v10, v4
	v_div_fmas_f32 v4, v4, v13, v10
	v_div_fixup_f32 v1, v4, v8, v1
	s_mov_b32 s3, 0x100000
	s_mov_b64 s[6:7], 0x100000
	s_waitcnt vmcnt(0)
	v_lshl_add_u64 v[2:3], v[2:3], 0, s[6:7]
	v_mov_b32_e32 v18, v6
	global_load_dwordx4 v[10:13], v18, s[8:9] offset:0
	global_load_dwordx4 v[14:17], v18, s[10:11] offset:0
	s_waitcnt vmcnt(0)
	v_mul_f32_e32 v4, v1, v14
	v_mul_f32_e32 v5, v1, v15
	v_mul_f32_e32 v6, v1, v16
	v_mul_f32_e32 v7, v1, v17
	v_fma_f32 v4, v9, v10, -v4
	v_fma_f32 v5, v9, v11, -v5
	v_fma_f32 v6, v9, v12, -v6
	v_fma_f32 v7, v9, v13, -v7
	v_mul_f32_e32 v14, v9, v14
	v_mul_f32_e32 v15, v9, v15
	v_mul_f32_e32 v16, v9, v16
	v_mul_f32_e32 v17, v9, v17
	v_fmac_f32_e32 v14, v1, v10
	v_fmac_f32_e32 v15, v1, v11
	v_fmac_f32_e32 v16, v1, v12
	v_fmac_f32_e32 v17, v1, v13
	global_store_dwordx4 v[2:3], v[4:7], off offset:0
	global_store_dwordx4 v[2:3], v[14:17], off offset:64
	global_load_dwordx4 v[10:13], v18, s[8:9] offset:16
	global_load_dwordx4 v[14:17], v18, s[10:11] offset:16
	s_waitcnt vmcnt(0)
	v_mul_f32_e32 v4, v1, v14
	v_mul_f32_e32 v5, v1, v15
	v_mul_f32_e32 v6, v1, v16
	v_mul_f32_e32 v7, v1, v17
	v_fma_f32 v4, v9, v10, -v4
	v_fma_f32 v5, v9, v11, -v5
	v_fma_f32 v6, v9, v12, -v6
	v_fma_f32 v7, v9, v13, -v7
	v_mul_f32_e32 v14, v9, v14
	v_mul_f32_e32 v15, v9, v15
	v_mul_f32_e32 v16, v9, v16
	v_mul_f32_e32 v17, v9, v17
	v_fmac_f32_e32 v14, v1, v10
	v_fmac_f32_e32 v15, v1, v11
	v_fmac_f32_e32 v16, v1, v12
	v_fmac_f32_e32 v17, v1, v13
	global_store_dwordx4 v[2:3], v[4:7], off offset:16
	global_store_dwordx4 v[2:3], v[14:17], off offset:80
	global_load_dwordx4 v[10:13], v18, s[8:9] offset:32
	global_load_dwordx4 v[14:17], v18, s[10:11] offset:32
	s_waitcnt vmcnt(0)
	v_mul_f32_e32 v4, v1, v14
	v_mul_f32_e32 v5, v1, v15
	v_mul_f32_e32 v6, v1, v16
	v_mul_f32_e32 v7, v1, v17
	v_fma_f32 v4, v9, v10, -v4
	v_fma_f32 v5, v9, v11, -v5
	v_fma_f32 v6, v9, v12, -v6
	v_fma_f32 v7, v9, v13, -v7
	v_mul_f32_e32 v14, v9, v14
	v_mul_f32_e32 v15, v9, v15
	v_mul_f32_e32 v16, v9, v16
	v_mul_f32_e32 v17, v9, v17
	v_fmac_f32_e32 v14, v1, v10
	v_fmac_f32_e32 v15, v1, v11
	v_fmac_f32_e32 v16, v1, v12
	v_fmac_f32_e32 v17, v1, v13
	global_store_dwordx4 v[2:3], v[4:7], off offset:32
	global_store_dwordx4 v[2:3], v[14:17], off offset:96
	global_load_dwordx4 v[10:13], v18, s[8:9] offset:48
	global_load_dwordx4 v[14:17], v18, s[10:11] offset:48
	s_waitcnt vmcnt(0)
	v_mul_f32_e32 v4, v1, v14
	v_mul_f32_e32 v5, v1, v15
	v_mul_f32_e32 v6, v1, v16
	v_mul_f32_e32 v7, v1, v17
	v_fma_f32 v4, v9, v10, -v4
	v_fma_f32 v5, v9, v11, -v5
	v_fma_f32 v6, v9, v12, -v6
	v_fma_f32 v7, v9, v13, -v7
	v_mul_f32_e32 v14, v9, v14
	v_mul_f32_e32 v15, v9, v15
	v_mul_f32_e32 v16, v9, v16
	v_mul_f32_e32 v17, v9, v17
	v_fmac_f32_e32 v14, v1, v10
	v_fmac_f32_e32 v15, v1, v11
	v_fmac_f32_e32 v16, v1, v12
	v_fmac_f32_e32 v17, v1, v13
	global_store_dwordx4 v[2:3], v[4:7], off offset:48
	global_store_dwordx4 v[2:3], v[14:17], off offset:112
